# scan compute block: per-lane dot as depth-3 tree (two accumulators + packed add), one dependent op fewer per step; on top of rms-loop pipelining
# speedup vs baseline: 1.0028x; 1.0028x over previous
.LBB0_1010:
	s_mov_b64 s[78:79], -1
	s_and_b64 vcc, exec, s[70:71]
	s_cbranch_vccz .LBB0_1014
	s_setprio 1
	s_and_b32 s55, s53, 1
	s_lshl_b32 s56, s55, 14
	s_mul_i32 s55, s55, 0xaa00
	v_or_b32_e32 v99, s56, v143
	v_lshl_add_u32 v96, v106, 2, s55
	v_lshl_add_u32 v97, v101, 2, s55
	v_mov_b32_e32 v98, s55
	v_add_u32_e32 v99, 0x15400, v99
	s_waitcnt vmcnt(0)
	ds_read_b128 v[170:173], v96 offset:256
	ds_read_b128 v[174:177], v96 offset:512
	ds_read_b128 v[166:169], v96
	ds_read_b128 v[182:185], v96 offset:1024
	ds_read_b128 v[178:181], v96 offset:768
	ds_read_b32 v186, v97 offset:1280
	ds_read_b64 v[188:189], v98 offset:1344
	ds_read_b128 v[194:197], v96 offset:1616
	ds_read_b128 v[198:201], v96 offset:1872
	ds_read_b128 v[190:193], v96 offset:1360
	ds_read_b128 v[206:209], v96 offset:2384
	ds_read_b128 v[202:205], v96 offset:2128
	ds_read_b32 v210, v97 offset:2640
	ds_read_b64 v[220:221], v98 offset:2704
	v_mov_b64_e32 v[48:49], v[92:93]
	v_mov_b64_e32 v[52:53], v[94:95]
	s_waitcnt lgkmcnt(7)
	v_pk_mul_f32 v[58:59], v[52:53], v[170:171] op_sel_hi:[0,1]
	v_pk_mul_f32 v[102:103], v[48:49], v[174:175] op_sel_hi:[0,1]
	ds_read_b128 v[32:35], v96 offset:2976
	ds_read_b128 v[36:39], v96 offset:3232
	v_pk_fma_f32 v[58:59], v[52:53], v[172:173], v[58:59] op_sel:[1,0,0]
	v_pk_fma_f32 v[102:103], v[48:49], v[176:177], v[102:103] op_sel:[1,0,0]
	ds_read_b128 v[28:31], v96 offset:2720
	ds_read_b128 v[44:47], v96 offset:3744
	ds_read_b128 v[40:43], v96 offset:3488
	v_pk_add_f32 v[58:59], v[58:59], v[102:103]
	v_pk_mul_f32 v[64:65], v[186:187], v[182:183] op_sel_hi:[0,1]
	v_pk_mul_f32 v[66:67], v[186:187], v[184:185] op_sel_hi:[0,1]
	v_add_f32_dpp v58, v58, v58 row_ror:8 row_mask:0xf bank_mask:0xf bound_ctrl:1
	v_pk_fma_f32 v[64:65], v[52:53], v[166:167], v[64:65]
	v_pk_fma_f32 v[66:67], v[48:49], v[168:169], v[66:67]
	v_add_f32_dpp v58, v58, v58 row_ror:4 row_mask:0xf bank_mask:0xf bound_ctrl:1
	v_add_f32_dpp v60, v59, v59 row_ror:8 row_mask:0xf bank_mask:0xf bound_ctrl:1
	s_nop 0
	v_add_f32_dpp v58, v58, v58 row_ror:2 row_mask:0xf bank_mask:0xf bound_ctrl:1
	v_fma_f32 v61, v186, v189, v60
	s_nop 0
	v_add_f32_dpp v58, v58, v58 row_ror:1 row_mask:0xf bank_mask:0xf bound_ctrl:1
	v_pk_fma_f32 v[52:53], v[58:59], v[178:179], v[64:65] op_sel_hi:[0,1,1]
	v_pk_fma_f32 v[48:49], v[58:59], v[180:181], v[66:67] op_sel_hi:[0,1,1]
	v_fma_f32 v61, v58, v188, v61
	ds_read_b32 v54, v97 offset:4000
	ds_read_b64 v[56:57], v98 offset:4064
	ds_write_b32 v99, v61
	s_waitcnt lgkmcnt(8)
	v_pk_mul_f32 v[58:59], v[52:53], v[194:195] op_sel_hi:[0,1]
	v_pk_mul_f32 v[102:103], v[48:49], v[198:199] op_sel_hi:[0,1]
	ds_read_b128 v[170:173], v96 offset:4336
	ds_read_b128 v[174:177], v96 offset:4592
	v_pk_fma_f32 v[58:59], v[52:53], v[196:197], v[58:59] op_sel:[1,0,0]
	v_pk_fma_f32 v[102:103], v[48:49], v[200:201], v[102:103] op_sel:[1,0,0]
	ds_read_b128 v[166:169], v96 offset:4080
	ds_read_b128 v[182:185], v96 offset:5104
	ds_read_b128 v[178:181], v96 offset:4848
	v_pk_add_f32 v[58:59], v[58:59], v[102:103]
	v_pk_mul_f32 v[64:65], v[210:211], v[206:207] op_sel_hi:[0,1]
	v_pk_mul_f32 v[66:67], v[210:211], v[208:209] op_sel_hi:[0,1]
	v_add_f32_dpp v58, v58, v58 row_ror:8 row_mask:0xf bank_mask:0xf bound_ctrl:1
	v_pk_fma_f32 v[64:65], v[52:53], v[190:191], v[64:65]
	v_pk_fma_f32 v[66:67], v[48:49], v[192:193], v[66:67]
	v_add_f32_dpp v58, v58, v58 row_ror:4 row_mask:0xf bank_mask:0xf bound_ctrl:1
	v_add_f32_dpp v60, v59, v59 row_ror:8 row_mask:0xf bank_mask:0xf bound_ctrl:1
	s_nop 0
	v_add_f32_dpp v58, v58, v58 row_ror:2 row_mask:0xf bank_mask:0xf bound_ctrl:1
	v_fma_f32 v61, v210, v221, v60
	s_nop 0
	v_add_f32_dpp v58, v58, v58 row_ror:1 row_mask:0xf bank_mask:0xf bound_ctrl:1
	v_pk_fma_f32 v[52:53], v[58:59], v[202:203], v[64:65] op_sel_hi:[0,1,1]
	v_pk_fma_f32 v[48:49], v[58:59], v[204:205], v[66:67] op_sel_hi:[0,1,1]
	v_fma_f32 v61, v58, v220, v61
	ds_read_b32 v186, v97 offset:5360
	ds_read_b64 v[188:189], v98 offset:5424
	ds_write_b32 v99, v61 offset:512
	s_waitcnt lgkmcnt(9)
	v_pk_mul_f32 v[58:59], v[52:53], v[32:33] op_sel_hi:[0,1]
	v_pk_mul_f32 v[102:103], v[48:49], v[36:37] op_sel_hi:[0,1]
	ds_read_b128 v[194:197], v96 offset:5696
	ds_read_b128 v[198:201], v96 offset:5952
	v_pk_fma_f32 v[58:59], v[52:53], v[34:35], v[58:59] op_sel:[1,0,0]
	v_pk_fma_f32 v[102:103], v[48:49], v[38:39], v[102:103] op_sel:[1,0,0]
	ds_read_b128 v[190:193], v96 offset:5440
	ds_read_b128 v[206:209], v96 offset:6464
	ds_read_b128 v[202:205], v96 offset:6208
	v_pk_add_f32 v[58:59], v[58:59], v[102:103]
	v_pk_mul_f32 v[64:65], v[54:55], v[44:45] op_sel_hi:[0,1]
	v_pk_mul_f32 v[66:67], v[54:55], v[46:47] op_sel_hi:[0,1]
	v_add_f32_dpp v58, v58, v58 row_ror:8 row_mask:0xf bank_mask:0xf bound_ctrl:1
	v_pk_fma_f32 v[64:65], v[52:53], v[28:29], v[64:65]
	v_pk_fma_f32 v[66:67], v[48:49], v[30:31], v[66:67]
	v_add_f32_dpp v58, v58, v58 row_ror:4 row_mask:0xf bank_mask:0xf bound_ctrl:1
	v_add_f32_dpp v60, v59, v59 row_ror:8 row_mask:0xf bank_mask:0xf bound_ctrl:1
	s_nop 0
	v_add_f32_dpp v58, v58, v58 row_ror:2 row_mask:0xf bank_mask:0xf bound_ctrl:1
	v_fma_f32 v61, v54, v57, v60
	s_nop 0
	v_add_f32_dpp v58, v58, v58 row_ror:1 row_mask:0xf bank_mask:0xf bound_ctrl:1
	v_pk_fma_f32 v[52:53], v[58:59], v[40:41], v[64:65] op_sel_hi:[0,1,1]
	v_pk_fma_f32 v[48:49], v[58:59], v[42:43], v[66:67] op_sel_hi:[0,1,1]
	v_fma_f32 v61, v58, v56, v61
	ds_read_b32 v210, v97 offset:6720
	ds_read_b64 v[220:221], v98 offset:6784
	ds_write_b32 v99, v61 offset:1024
	s_waitcnt lgkmcnt(9)
	v_pk_mul_f32 v[58:59], v[52:53], v[170:171] op_sel_hi:[0,1]
	v_pk_mul_f32 v[102:103], v[48:49], v[174:175] op_sel_hi:[0,1]
	ds_read_b128 v[32:35], v96 offset:7056
	ds_read_b128 v[36:39], v96 offset:7312
	v_pk_fma_f32 v[58:59], v[52:53], v[172:173], v[58:59] op_sel:[1,0,0]
	v_pk_fma_f32 v[102:103], v[48:49], v[176:177], v[102:103] op_sel:[1,0,0]
	ds_read_b128 v[28:31], v96 offset:6800
	ds_read_b128 v[44:47], v96 offset:7824
	ds_read_b128 v[40:43], v96 offset:7568
	v_pk_add_f32 v[58:59], v[58:59], v[102:103]
	v_pk_mul_f32 v[64:65], v[186:187], v[182:183] op_sel_hi:[0,1]
	v_pk_mul_f32 v[66:67], v[186:187], v[184:185] op_sel_hi:[0,1]
	v_add_f32_dpp v58, v58, v58 row_ror:8 row_mask:0xf bank_mask:0xf bound_ctrl:1
	v_pk_fma_f32 v[64:65], v[52:53], v[166:167], v[64:65]
	v_pk_fma_f32 v[66:67], v[48:49], v[168:169], v[66:67]
	v_add_f32_dpp v58, v58, v58 row_ror:4 row_mask:0xf bank_mask:0xf bound_ctrl:1
	v_add_f32_dpp v60, v59, v59 row_ror:8 row_mask:0xf bank_mask:0xf bound_ctrl:1
	s_nop 0
	v_add_f32_dpp v58, v58, v58 row_ror:2 row_mask:0xf bank_mask:0xf bound_ctrl:1
	v_fma_f32 v61, v186, v189, v60
	s_nop 0
	v_add_f32_dpp v58, v58, v58 row_ror:1 row_mask:0xf bank_mask:0xf bound_ctrl:1
	v_pk_fma_f32 v[52:53], v[58:59], v[178:179], v[64:65] op_sel_hi:[0,1,1]
	v_pk_fma_f32 v[48:49], v[58:59], v[180:181], v[66:67] op_sel_hi:[0,1,1]
	v_fma_f32 v61, v58, v188, v61
	ds_read_b32 v54, v97 offset:8080
	ds_read_b64 v[56:57], v98 offset:8144
	ds_write_b32 v99, v61 offset:1536
	s_waitcnt lgkmcnt(9)
	v_pk_mul_f32 v[58:59], v[52:53], v[194:195] op_sel_hi:[0,1]
	v_pk_mul_f32 v[102:103], v[48:49], v[198:199] op_sel_hi:[0,1]
	ds_read_b128 v[170:173], v96 offset:8416
	ds_read_b128 v[174:177], v96 offset:8672
	v_pk_fma_f32 v[58:59], v[52:53], v[196:197], v[58:59] op_sel:[1,0,0]
	v_pk_fma_f32 v[102:103], v[48:49], v[200:201], v[102:103] op_sel:[1,0,0]
	ds_read_b128 v[166:169], v96 offset:8160
	ds_read_b128 v[182:185], v96 offset:9184
	ds_read_b128 v[178:181], v96 offset:8928
	v_pk_add_f32 v[58:59], v[58:59], v[102:103]
	v_pk_mul_f32 v[64:65], v[210:211], v[206:207] op_sel_hi:[0,1]
	v_pk_mul_f32 v[66:67], v[210:211], v[208:209] op_sel_hi:[0,1]
	v_add_f32_dpp v58, v58, v58 row_ror:8 row_mask:0xf bank_mask:0xf bound_ctrl:1
	v_pk_fma_f32 v[64:65], v[52:53], v[190:191], v[64:65]
	v_pk_fma_f32 v[66:67], v[48:49], v[192:193], v[66:67]
	v_add_f32_dpp v58, v58, v58 row_ror:4 row_mask:0xf bank_mask:0xf bound_ctrl:1
	v_add_f32_dpp v60, v59, v59 row_ror:8 row_mask:0xf bank_mask:0xf bound_ctrl:1
	s_nop 0
	v_add_f32_dpp v58, v58, v58 row_ror:2 row_mask:0xf bank_mask:0xf bound_ctrl:1
	v_fma_f32 v61, v210, v221, v60
	s_nop 0
	v_add_f32_dpp v58, v58, v58 row_ror:1 row_mask:0xf bank_mask:0xf bound_ctrl:1
	v_pk_fma_f32 v[52:53], v[58:59], v[202:203], v[64:65] op_sel_hi:[0,1,1]
	v_pk_fma_f32 v[48:49], v[58:59], v[204:205], v[66:67] op_sel_hi:[0,1,1]
	v_fma_f32 v61, v58, v220, v61
	ds_read_b32 v186, v97 offset:9440
	ds_read_b64 v[188:189], v98 offset:9504
	ds_write_b32 v99, v61 offset:2048
	s_waitcnt lgkmcnt(9)
	v_pk_mul_f32 v[58:59], v[52:53], v[32:33] op_sel_hi:[0,1]
	v_pk_mul_f32 v[102:103], v[48:49], v[36:37] op_sel_hi:[0,1]
	ds_read_b128 v[194:197], v96 offset:9776
	ds_read_b128 v[198:201], v96 offset:10032
	v_pk_fma_f32 v[58:59], v[52:53], v[34:35], v[58:59] op_sel:[1,0,0]
	v_pk_fma_f32 v[102:103], v[48:49], v[38:39], v[102:103] op_sel:[1,0,0]
	ds_read_b128 v[190:193], v96 offset:9520
	ds_read_b128 v[206:209], v96 offset:10544
	ds_read_b128 v[202:205], v96 offset:10288
	v_pk_add_f32 v[58:59], v[58:59], v[102:103]
	v_pk_mul_f32 v[64:65], v[54:55], v[44:45] op_sel_hi:[0,1]
	v_pk_mul_f32 v[66:67], v[54:55], v[46:47] op_sel_hi:[0,1]
	v_add_f32_dpp v58, v58, v58 row_ror:8 row_mask:0xf bank_mask:0xf bound_ctrl:1
	v_pk_fma_f32 v[64:65], v[52:53], v[28:29], v[64:65]
	v_pk_fma_f32 v[66:67], v[48:49], v[30:31], v[66:67]
	v_add_f32_dpp v58, v58, v58 row_ror:4 row_mask:0xf bank_mask:0xf bound_ctrl:1
	v_add_f32_dpp v60, v59, v59 row_ror:8 row_mask:0xf bank_mask:0xf bound_ctrl:1
	s_nop 0
	v_add_f32_dpp v58, v58, v58 row_ror:2 row_mask:0xf bank_mask:0xf bound_ctrl:1
	v_fma_f32 v61, v54, v57, v60
	s_nop 0
	v_add_f32_dpp v58, v58, v58 row_ror:1 row_mask:0xf bank_mask:0xf bound_ctrl:1
	v_pk_fma_f32 v[52:53], v[58:59], v[40:41], v[64:65] op_sel_hi:[0,1,1]
	v_pk_fma_f32 v[48:49], v[58:59], v[42:43], v[66:67] op_sel_hi:[0,1,1]
	v_fma_f32 v61, v58, v56, v61
	ds_read_b32 v210, v97 offset:10800
	ds_read_b64 v[220:221], v98 offset:10864
	ds_write_b32 v99, v61 offset:2560
	s_waitcnt lgkmcnt(9)
	v_pk_mul_f32 v[58:59], v[52:53], v[170:171] op_sel_hi:[0,1]
	v_pk_mul_f32 v[102:103], v[48:49], v[174:175] op_sel_hi:[0,1]
	ds_read_b128 v[32:35], v96 offset:11136
	ds_read_b128 v[36:39], v96 offset:11392
	v_pk_fma_f32 v[58:59], v[52:53], v[172:173], v[58:59] op_sel:[1,0,0]
	v_pk_fma_f32 v[102:103], v[48:49], v[176:177], v[102:103] op_sel:[1,0,0]
	ds_read_b128 v[28:31], v96 offset:10880
	ds_read_b128 v[44:47], v96 offset:11904
	ds_read_b128 v[40:43], v96 offset:11648
	v_pk_add_f32 v[58:59], v[58:59], v[102:103]
	v_pk_mul_f32 v[64:65], v[186:187], v[182:183] op_sel_hi:[0,1]
	v_pk_mul_f32 v[66:67], v[186:187], v[184:185] op_sel_hi:[0,1]
	v_add_f32_dpp v58, v58, v58 row_ror:8 row_mask:0xf bank_mask:0xf bound_ctrl:1
	v_pk_fma_f32 v[64:65], v[52:53], v[166:167], v[64:65]
	v_pk_fma_f32 v[66:67], v[48:49], v[168:169], v[66:67]
	v_add_f32_dpp v58, v58, v58 row_ror:4 row_mask:0xf bank_mask:0xf bound_ctrl:1
	v_add_f32_dpp v60, v59, v59 row_ror:8 row_mask:0xf bank_mask:0xf bound_ctrl:1
	s_nop 0
	v_add_f32_dpp v58, v58, v58 row_ror:2 row_mask:0xf bank_mask:0xf bound_ctrl:1
	v_fma_f32 v61, v186, v189, v60
	s_nop 0
	v_add_f32_dpp v58, v58, v58 row_ror:1 row_mask:0xf bank_mask:0xf bound_ctrl:1
	v_pk_fma_f32 v[52:53], v[58:59], v[178:179], v[64:65] op_sel_hi:[0,1,1]
	v_pk_fma_f32 v[48:49], v[58:59], v[180:181], v[66:67] op_sel_hi:[0,1,1]
	v_fma_f32 v61, v58, v188, v61
	ds_read_b32 v54, v97 offset:12160
	ds_read_b64 v[56:57], v98 offset:12224
	ds_write_b32 v99, v61 offset:3072
	s_waitcnt lgkmcnt(9)
	v_pk_mul_f32 v[58:59], v[52:53], v[194:195] op_sel_hi:[0,1]
	v_pk_mul_f32 v[102:103], v[48:49], v[198:199] op_sel_hi:[0,1]
	ds_read_b128 v[170:173], v96 offset:12496
	ds_read_b128 v[174:177], v96 offset:12752
	v_pk_fma_f32 v[58:59], v[52:53], v[196:197], v[58:59] op_sel:[1,0,0]
	v_pk_fma_f32 v[102:103], v[48:49], v[200:201], v[102:103] op_sel:[1,0,0]
	ds_read_b128 v[166:169], v96 offset:12240
	ds_read_b128 v[182:185], v96 offset:13264
	ds_read_b128 v[178:181], v96 offset:13008
	v_pk_add_f32 v[58:59], v[58:59], v[102:103]
	v_pk_mul_f32 v[64:65], v[210:211], v[206:207] op_sel_hi:[0,1]
	v_pk_mul_f32 v[66:67], v[210:211], v[208:209] op_sel_hi:[0,1]
	v_add_f32_dpp v58, v58, v58 row_ror:8 row_mask:0xf bank_mask:0xf bound_ctrl:1
	v_pk_fma_f32 v[64:65], v[52:53], v[190:191], v[64:65]
	v_pk_fma_f32 v[66:67], v[48:49], v[192:193], v[66:67]
	v_add_f32_dpp v58, v58, v58 row_ror:4 row_mask:0xf bank_mask:0xf bound_ctrl:1
	v_add_f32_dpp v60, v59, v59 row_ror:8 row_mask:0xf bank_mask:0xf bound_ctrl:1
	s_nop 0
	v_add_f32_dpp v58, v58, v58 row_ror:2 row_mask:0xf bank_mask:0xf bound_ctrl:1
	v_fma_f32 v61, v210, v221, v60
	s_nop 0
	v_add_f32_dpp v58, v58, v58 row_ror:1 row_mask:0xf bank_mask:0xf bound_ctrl:1
	v_pk_fma_f32 v[52:53], v[58:59], v[202:203], v[64:65] op_sel_hi:[0,1,1]
	v_pk_fma_f32 v[48:49], v[58:59], v[204:205], v[66:67] op_sel_hi:[0,1,1]
	v_fma_f32 v61, v58, v220, v61
	ds_read_b32 v186, v97 offset:13520
	ds_read_b64 v[188:189], v98 offset:13584
	ds_write_b32 v99, v61 offset:3584
	s_waitcnt lgkmcnt(9)
	v_pk_mul_f32 v[58:59], v[52:53], v[32:33] op_sel_hi:[0,1]
	v_pk_mul_f32 v[102:103], v[48:49], v[36:37] op_sel_hi:[0,1]
	ds_read_b128 v[194:197], v96 offset:13856
	ds_read_b128 v[198:201], v96 offset:14112
	v_pk_fma_f32 v[58:59], v[52:53], v[34:35], v[58:59] op_sel:[1,0,0]
	v_pk_fma_f32 v[102:103], v[48:49], v[38:39], v[102:103] op_sel:[1,0,0]
	ds_read_b128 v[190:193], v96 offset:13600
	ds_read_b128 v[206:209], v96 offset:14624
	ds_read_b128 v[202:205], v96 offset:14368
	v_pk_add_f32 v[58:59], v[58:59], v[102:103]
	v_pk_mul_f32 v[64:65], v[54:55], v[44:45] op_sel_hi:[0,1]
	v_pk_mul_f32 v[66:67], v[54:55], v[46:47] op_sel_hi:[0,1]
	v_add_f32_dpp v58, v58, v58 row_ror:8 row_mask:0xf bank_mask:0xf bound_ctrl:1
	v_pk_fma_f32 v[64:65], v[52:53], v[28:29], v[64:65]
	v_pk_fma_f32 v[66:67], v[48:49], v[30:31], v[66:67]
	v_add_f32_dpp v58, v58, v58 row_ror:4 row_mask:0xf bank_mask:0xf bound_ctrl:1
	v_add_f32_dpp v60, v59, v59 row_ror:8 row_mask:0xf bank_mask:0xf bound_ctrl:1
	s_nop 0
	v_add_f32_dpp v58, v58, v58 row_ror:2 row_mask:0xf bank_mask:0xf bound_ctrl:1
	v_fma_f32 v61, v54, v57, v60
	s_nop 0
	v_add_f32_dpp v58, v58, v58 row_ror:1 row_mask:0xf bank_mask:0xf bound_ctrl:1
	v_pk_fma_f32 v[52:53], v[58:59], v[40:41], v[64:65] op_sel_hi:[0,1,1]
	v_pk_fma_f32 v[48:49], v[58:59], v[42:43], v[66:67] op_sel_hi:[0,1,1]
	v_fma_f32 v61, v58, v56, v61
	ds_read_b32 v210, v97 offset:14880
	ds_read_b64 v[220:221], v98 offset:14944
	ds_write_b32 v99, v61 offset:4096
	s_waitcnt lgkmcnt(9)
	v_pk_mul_f32 v[58:59], v[52:53], v[170:171] op_sel_hi:[0,1]
	v_pk_mul_f32 v[102:103], v[48:49], v[174:175] op_sel_hi:[0,1]
	ds_read_b128 v[32:35], v96 offset:15216
	ds_read_b128 v[36:39], v96 offset:15472
	v_pk_fma_f32 v[58:59], v[52:53], v[172:173], v[58:59] op_sel:[1,0,0]
	v_pk_fma_f32 v[102:103], v[48:49], v[176:177], v[102:103] op_sel:[1,0,0]
	ds_read_b128 v[28:31], v96 offset:14960
	ds_read_b128 v[44:47], v96 offset:15984
	ds_read_b128 v[40:43], v96 offset:15728
	v_pk_add_f32 v[58:59], v[58:59], v[102:103]
	v_pk_mul_f32 v[64:65], v[186:187], v[182:183] op_sel_hi:[0,1]
	v_pk_mul_f32 v[66:67], v[186:187], v[184:185] op_sel_hi:[0,1]
	v_add_f32_dpp v58, v58, v58 row_ror:8 row_mask:0xf bank_mask:0xf bound_ctrl:1
	v_pk_fma_f32 v[64:65], v[52:53], v[166:167], v[64:65]
	v_pk_fma_f32 v[66:67], v[48:49], v[168:169], v[66:67]
	v_add_f32_dpp v58, v58, v58 row_ror:4 row_mask:0xf bank_mask:0xf bound_ctrl:1
	v_add_f32_dpp v60, v59, v59 row_ror:8 row_mask:0xf bank_mask:0xf bound_ctrl:1
	s_nop 0
	v_add_f32_dpp v58, v58, v58 row_ror:2 row_mask:0xf bank_mask:0xf bound_ctrl:1
	v_fma_f32 v61, v186, v189, v60
	s_nop 0
	v_add_f32_dpp v58, v58, v58 row_ror:1 row_mask:0xf bank_mask:0xf bound_ctrl:1
	v_pk_fma_f32 v[52:53], v[58:59], v[178:179], v[64:65] op_sel_hi:[0,1,1]
	v_pk_fma_f32 v[48:49], v[58:59], v[180:181], v[66:67] op_sel_hi:[0,1,1]
	v_fma_f32 v61, v58, v188, v61
	ds_read_b32 v54, v97 offset:16240
	ds_read_b64 v[56:57], v98 offset:16304
	ds_write_b32 v99, v61 offset:4608
	s_waitcnt lgkmcnt(9)
	v_pk_mul_f32 v[58:59], v[52:53], v[194:195] op_sel_hi:[0,1]
	v_pk_mul_f32 v[102:103], v[48:49], v[198:199] op_sel_hi:[0,1]
	ds_read_b128 v[170:173], v96 offset:16576
	ds_read_b128 v[174:177], v96 offset:16832
	v_pk_fma_f32 v[58:59], v[52:53], v[196:197], v[58:59] op_sel:[1,0,0]
	v_pk_fma_f32 v[102:103], v[48:49], v[200:201], v[102:103] op_sel:[1,0,0]
	ds_read_b128 v[166:169], v96 offset:16320
	ds_read_b128 v[182:185], v96 offset:17344
	ds_read_b128 v[178:181], v96 offset:17088
	v_pk_add_f32 v[58:59], v[58:59], v[102:103]
	v_pk_mul_f32 v[64:65], v[210:211], v[206:207] op_sel_hi:[0,1]
	v_pk_mul_f32 v[66:67], v[210:211], v[208:209] op_sel_hi:[0,1]
	v_add_f32_dpp v58, v58, v58 row_ror:8 row_mask:0xf bank_mask:0xf bound_ctrl:1
	v_pk_fma_f32 v[64:65], v[52:53], v[190:191], v[64:65]
	v_pk_fma_f32 v[66:67], v[48:49], v[192:193], v[66:67]
	v_add_f32_dpp v58, v58, v58 row_ror:4 row_mask:0xf bank_mask:0xf bound_ctrl:1
	v_add_f32_dpp v60, v59, v59 row_ror:8 row_mask:0xf bank_mask:0xf bound_ctrl:1
	s_nop 0
	v_add_f32_dpp v58, v58, v58 row_ror:2 row_mask:0xf bank_mask:0xf bound_ctrl:1
	v_fma_f32 v61, v210, v221, v60
	s_nop 0
	v_add_f32_dpp v58, v58, v58 row_ror:1 row_mask:0xf bank_mask:0xf bound_ctrl:1
	v_pk_fma_f32 v[52:53], v[58:59], v[202:203], v[64:65] op_sel_hi:[0,1,1]
	v_pk_fma_f32 v[48:49], v[58:59], v[204:205], v[66:67] op_sel_hi:[0,1,1]
	v_fma_f32 v61, v58, v220, v61
	ds_read_b32 v186, v97 offset:17600
	ds_read_b64 v[188:189], v98 offset:17664
	ds_write_b32 v99, v61 offset:5120
	s_waitcnt lgkmcnt(9)
	v_pk_mul_f32 v[58:59], v[52:53], v[32:33] op_sel_hi:[0,1]
	v_pk_mul_f32 v[102:103], v[48:49], v[36:37] op_sel_hi:[0,1]
	ds_read_b128 v[194:197], v96 offset:17936
	ds_read_b128 v[198:201], v96 offset:18192
	v_pk_fma_f32 v[58:59], v[52:53], v[34:35], v[58:59] op_sel:[1,0,0]
	v_pk_fma_f32 v[102:103], v[48:49], v[38:39], v[102:103] op_sel:[1,0,0]
	ds_read_b128 v[190:193], v96 offset:17680
	ds_read_b128 v[206:209], v96 offset:18704
	ds_read_b128 v[202:205], v96 offset:18448
	v_pk_add_f32 v[58:59], v[58:59], v[102:103]
	v_pk_mul_f32 v[64:65], v[54:55], v[44:45] op_sel_hi:[0,1]
	v_pk_mul_f32 v[66:67], v[54:55], v[46:47] op_sel_hi:[0,1]
	v_add_f32_dpp v58, v58, v58 row_ror:8 row_mask:0xf bank_mask:0xf bound_ctrl:1
	v_pk_fma_f32 v[64:65], v[52:53], v[28:29], v[64:65]
	v_pk_fma_f32 v[66:67], v[48:49], v[30:31], v[66:67]
	v_add_f32_dpp v58, v58, v58 row_ror:4 row_mask:0xf bank_mask:0xf bound_ctrl:1
	v_add_f32_dpp v60, v59, v59 row_ror:8 row_mask:0xf bank_mask:0xf bound_ctrl:1
	s_nop 0
	v_add_f32_dpp v58, v58, v58 row_ror:2 row_mask:0xf bank_mask:0xf bound_ctrl:1
	v_fma_f32 v61, v54, v57, v60
	s_nop 0
	v_add_f32_dpp v58, v58, v58 row_ror:1 row_mask:0xf bank_mask:0xf bound_ctrl:1
	v_pk_fma_f32 v[52:53], v[58:59], v[40:41], v[64:65] op_sel_hi:[0,1,1]
	v_pk_fma_f32 v[48:49], v[58:59], v[42:43], v[66:67] op_sel_hi:[0,1,1]
	v_fma_f32 v61, v58, v56, v61
	ds_read_b32 v210, v97 offset:18960
	ds_read_b64 v[220:221], v98 offset:19024
	ds_write_b32 v99, v61 offset:5632
	s_waitcnt lgkmcnt(9)
	v_pk_mul_f32 v[58:59], v[52:53], v[170:171] op_sel_hi:[0,1]
	v_pk_mul_f32 v[102:103], v[48:49], v[174:175] op_sel_hi:[0,1]
	ds_read_b128 v[32:35], v96 offset:19296
	ds_read_b128 v[36:39], v96 offset:19552
	v_pk_fma_f32 v[58:59], v[52:53], v[172:173], v[58:59] op_sel:[1,0,0]
	v_pk_fma_f32 v[102:103], v[48:49], v[176:177], v[102:103] op_sel:[1,0,0]
	ds_read_b128 v[28:31], v96 offset:19040
	ds_read_b128 v[44:47], v96 offset:20064
	ds_read_b128 v[40:43], v96 offset:19808
	v_pk_add_f32 v[58:59], v[58:59], v[102:103]
	v_pk_mul_f32 v[64:65], v[186:187], v[182:183] op_sel_hi:[0,1]
	v_pk_mul_f32 v[66:67], v[186:187], v[184:185] op_sel_hi:[0,1]
	v_add_f32_dpp v58, v58, v58 row_ror:8 row_mask:0xf bank_mask:0xf bound_ctrl:1
	v_pk_fma_f32 v[64:65], v[52:53], v[166:167], v[64:65]
	v_pk_fma_f32 v[66:67], v[48:49], v[168:169], v[66:67]
	v_add_f32_dpp v58, v58, v58 row_ror:4 row_mask:0xf bank_mask:0xf bound_ctrl:1
	v_add_f32_dpp v60, v59, v59 row_ror:8 row_mask:0xf bank_mask:0xf bound_ctrl:1
	s_nop 0
	v_add_f32_dpp v58, v58, v58 row_ror:2 row_mask:0xf bank_mask:0xf bound_ctrl:1
	v_fma_f32 v61, v186, v189, v60
	s_nop 0
	v_add_f32_dpp v58, v58, v58 row_ror:1 row_mask:0xf bank_mask:0xf bound_ctrl:1
	v_pk_fma_f32 v[52:53], v[58:59], v[178:179], v[64:65] op_sel_hi:[0,1,1]
	v_pk_fma_f32 v[48:49], v[58:59], v[180:181], v[66:67] op_sel_hi:[0,1,1]
	v_fma_f32 v61, v58, v188, v61
	ds_read_b32 v54, v97 offset:20320
	ds_read_b64 v[56:57], v98 offset:20384
	ds_write_b32 v99, v61 offset:6144
	s_waitcnt lgkmcnt(9)
	v_pk_mul_f32 v[58:59], v[52:53], v[194:195] op_sel_hi:[0,1]
	v_pk_mul_f32 v[102:103], v[48:49], v[198:199] op_sel_hi:[0,1]
	ds_read_b128 v[170:173], v96 offset:20656
	ds_read_b128 v[174:177], v96 offset:20912
	v_pk_fma_f32 v[58:59], v[52:53], v[196:197], v[58:59] op_sel:[1,0,0]
	v_pk_fma_f32 v[102:103], v[48:49], v[200:201], v[102:103] op_sel:[1,0,0]
	ds_read_b128 v[166:169], v96 offset:20400
	ds_read_b128 v[182:185], v96 offset:21424
	ds_read_b128 v[178:181], v96 offset:21168
	v_pk_add_f32 v[58:59], v[58:59], v[102:103]
	v_pk_mul_f32 v[64:65], v[210:211], v[206:207] op_sel_hi:[0,1]
	v_pk_mul_f32 v[66:67], v[210:211], v[208:209] op_sel_hi:[0,1]
	v_add_f32_dpp v58, v58, v58 row_ror:8 row_mask:0xf bank_mask:0xf bound_ctrl:1
	v_pk_fma_f32 v[64:65], v[52:53], v[190:191], v[64:65]
	v_pk_fma_f32 v[66:67], v[48:49], v[192:193], v[66:67]
	v_add_f32_dpp v58, v58, v58 row_ror:4 row_mask:0xf bank_mask:0xf bound_ctrl:1
	v_add_f32_dpp v60, v59, v59 row_ror:8 row_mask:0xf bank_mask:0xf bound_ctrl:1
	s_nop 0
	v_add_f32_dpp v58, v58, v58 row_ror:2 row_mask:0xf bank_mask:0xf bound_ctrl:1
	v_fma_f32 v61, v210, v221, v60
	s_nop 0
	v_add_f32_dpp v58, v58, v58 row_ror:1 row_mask:0xf bank_mask:0xf bound_ctrl:1
	v_pk_fma_f32 v[52:53], v[58:59], v[202:203], v[64:65] op_sel_hi:[0,1,1]
	v_pk_fma_f32 v[48:49], v[58:59], v[204:205], v[66:67] op_sel_hi:[0,1,1]
	v_fma_f32 v61, v58, v220, v61
	ds_read_b32 v186, v97 offset:21680
	ds_read_b64 v[188:189], v98 offset:21744
	ds_write_b32 v99, v61 offset:6656
	s_waitcnt lgkmcnt(9)
	v_pk_mul_f32 v[58:59], v[52:53], v[32:33] op_sel_hi:[0,1]
	v_pk_mul_f32 v[102:103], v[48:49], v[36:37] op_sel_hi:[0,1]
	ds_read_b128 v[194:197], v96 offset:22016
	ds_read_b128 v[198:201], v96 offset:22272
	v_pk_fma_f32 v[58:59], v[52:53], v[34:35], v[58:59] op_sel:[1,0,0]
	v_pk_fma_f32 v[102:103], v[48:49], v[38:39], v[102:103] op_sel:[1,0,0]
	ds_read_b128 v[190:193], v96 offset:21760
	ds_read_b128 v[206:209], v96 offset:22784
	ds_read_b128 v[202:205], v96 offset:22528
	v_pk_add_f32 v[58:59], v[58:59], v[102:103]
	v_pk_mul_f32 v[64:65], v[54:55], v[44:45] op_sel_hi:[0,1]
	v_pk_mul_f32 v[66:67], v[54:55], v[46:47] op_sel_hi:[0,1]
	v_add_f32_dpp v58, v58, v58 row_ror:8 row_mask:0xf bank_mask:0xf bound_ctrl:1
	v_pk_fma_f32 v[64:65], v[52:53], v[28:29], v[64:65]
	v_pk_fma_f32 v[66:67], v[48:49], v[30:31], v[66:67]
	v_add_f32_dpp v58, v58, v58 row_ror:4 row_mask:0xf bank_mask:0xf bound_ctrl:1
	v_add_f32_dpp v60, v59, v59 row_ror:8 row_mask:0xf bank_mask:0xf bound_ctrl:1
	s_nop 0
	v_add_f32_dpp v58, v58, v58 row_ror:2 row_mask:0xf bank_mask:0xf bound_ctrl:1
	v_fma_f32 v61, v54, v57, v60
	s_nop 0
	v_add_f32_dpp v58, v58, v58 row_ror:1 row_mask:0xf bank_mask:0xf bound_ctrl:1
	v_pk_fma_f32 v[52:53], v[58:59], v[40:41], v[64:65] op_sel_hi:[0,1,1]
	v_pk_fma_f32 v[48:49], v[58:59], v[42:43], v[66:67] op_sel_hi:[0,1,1]
	v_fma_f32 v61, v58, v56, v61
	ds_read_b32 v210, v97 offset:23040
	ds_read_b64 v[220:221], v98 offset:23104
	ds_write_b32 v99, v61 offset:7168
	s_waitcnt lgkmcnt(9)
	v_pk_mul_f32 v[58:59], v[52:53], v[170:171] op_sel_hi:[0,1]
	v_pk_mul_f32 v[102:103], v[48:49], v[174:175] op_sel_hi:[0,1]
	ds_read_b128 v[32:35], v96 offset:23376
	ds_read_b128 v[36:39], v96 offset:23632
	v_pk_fma_f32 v[58:59], v[52:53], v[172:173], v[58:59] op_sel:[1,0,0]
	v_pk_fma_f32 v[102:103], v[48:49], v[176:177], v[102:103] op_sel:[1,0,0]
	ds_read_b128 v[28:31], v96 offset:23120
	ds_read_b128 v[44:47], v96 offset:24144
	ds_read_b128 v[40:43], v96 offset:23888
	v_pk_add_f32 v[58:59], v[58:59], v[102:103]
	v_pk_mul_f32 v[64:65], v[186:187], v[182:183] op_sel_hi:[0,1]
	v_pk_mul_f32 v[66:67], v[186:187], v[184:185] op_sel_hi:[0,1]
	v_add_f32_dpp v58, v58, v58 row_ror:8 row_mask:0xf bank_mask:0xf bound_ctrl:1
	v_pk_fma_f32 v[64:65], v[52:53], v[166:167], v[64:65]
	v_pk_fma_f32 v[66:67], v[48:49], v[168:169], v[66:67]
	v_add_f32_dpp v58, v58, v58 row_ror:4 row_mask:0xf bank_mask:0xf bound_ctrl:1
	v_add_f32_dpp v60, v59, v59 row_ror:8 row_mask:0xf bank_mask:0xf bound_ctrl:1
	s_nop 0
	v_add_f32_dpp v58, v58, v58 row_ror:2 row_mask:0xf bank_mask:0xf bound_ctrl:1
	v_fma_f32 v61, v186, v189, v60
	s_nop 0
	v_add_f32_dpp v58, v58, v58 row_ror:1 row_mask:0xf bank_mask:0xf bound_ctrl:1
	v_pk_fma_f32 v[52:53], v[58:59], v[178:179], v[64:65] op_sel_hi:[0,1,1]
	v_pk_fma_f32 v[48:49], v[58:59], v[180:181], v[66:67] op_sel_hi:[0,1,1]
	v_fma_f32 v61, v58, v188, v61
	ds_read_b32 v54, v97 offset:24400
	ds_read_b64 v[56:57], v98 offset:24464
	ds_write_b32 v99, v61 offset:7680
	s_waitcnt lgkmcnt(9)
	v_pk_mul_f32 v[58:59], v[52:53], v[194:195] op_sel_hi:[0,1]
	v_pk_mul_f32 v[102:103], v[48:49], v[198:199] op_sel_hi:[0,1]
	ds_read_b128 v[170:173], v96 offset:24736
	ds_read_b128 v[174:177], v96 offset:24992
	v_pk_fma_f32 v[58:59], v[52:53], v[196:197], v[58:59] op_sel:[1,0,0]
	v_pk_fma_f32 v[102:103], v[48:49], v[200:201], v[102:103] op_sel:[1,0,0]
	ds_read_b128 v[166:169], v96 offset:24480
	ds_read_b128 v[182:185], v96 offset:25504
	ds_read_b128 v[178:181], v96 offset:25248
	v_pk_add_f32 v[58:59], v[58:59], v[102:103]
	v_pk_mul_f32 v[64:65], v[210:211], v[206:207] op_sel_hi:[0,1]
	v_pk_mul_f32 v[66:67], v[210:211], v[208:209] op_sel_hi:[0,1]
	v_add_f32_dpp v58, v58, v58 row_ror:8 row_mask:0xf bank_mask:0xf bound_ctrl:1
	v_pk_fma_f32 v[64:65], v[52:53], v[190:191], v[64:65]
	v_pk_fma_f32 v[66:67], v[48:49], v[192:193], v[66:67]
	v_add_f32_dpp v58, v58, v58 row_ror:4 row_mask:0xf bank_mask:0xf bound_ctrl:1
	v_add_f32_dpp v60, v59, v59 row_ror:8 row_mask:0xf bank_mask:0xf bound_ctrl:1
	s_nop 0
	v_add_f32_dpp v58, v58, v58 row_ror:2 row_mask:0xf bank_mask:0xf bound_ctrl:1
	v_fma_f32 v61, v210, v221, v60
	s_nop 0
	v_add_f32_dpp v58, v58, v58 row_ror:1 row_mask:0xf bank_mask:0xf bound_ctrl:1
	v_pk_fma_f32 v[52:53], v[58:59], v[202:203], v[64:65] op_sel_hi:[0,1,1]
	v_pk_fma_f32 v[48:49], v[58:59], v[204:205], v[66:67] op_sel_hi:[0,1,1]
	v_fma_f32 v61, v58, v220, v61
	ds_read_b32 v186, v97 offset:25760
	ds_read_b64 v[188:189], v98 offset:25824
	ds_write_b32 v99, v61 offset:8192
	s_waitcnt lgkmcnt(9)
	v_pk_mul_f32 v[58:59], v[52:53], v[32:33] op_sel_hi:[0,1]
	v_pk_mul_f32 v[102:103], v[48:49], v[36:37] op_sel_hi:[0,1]
	ds_read_b128 v[194:197], v96 offset:26096
	ds_read_b128 v[198:201], v96 offset:26352
	v_pk_fma_f32 v[58:59], v[52:53], v[34:35], v[58:59] op_sel:[1,0,0]
	v_pk_fma_f32 v[102:103], v[48:49], v[38:39], v[102:103] op_sel:[1,0,0]
	ds_read_b128 v[190:193], v96 offset:25840
	ds_read_b128 v[206:209], v96 offset:26864
	ds_read_b128 v[202:205], v96 offset:26608
	v_pk_add_f32 v[58:59], v[58:59], v[102:103]
	v_pk_mul_f32 v[64:65], v[54:55], v[44:45] op_sel_hi:[0,1]
	v_pk_mul_f32 v[66:67], v[54:55], v[46:47] op_sel_hi:[0,1]
	v_add_f32_dpp v58, v58, v58 row_ror:8 row_mask:0xf bank_mask:0xf bound_ctrl:1
	v_pk_fma_f32 v[64:65], v[52:53], v[28:29], v[64:65]
	v_pk_fma_f32 v[66:67], v[48:49], v[30:31], v[66:67]
	v_add_f32_dpp v58, v58, v58 row_ror:4 row_mask:0xf bank_mask:0xf bound_ctrl:1
	v_add_f32_dpp v60, v59, v59 row_ror:8 row_mask:0xf bank_mask:0xf bound_ctrl:1
	s_nop 0
	v_add_f32_dpp v58, v58, v58 row_ror:2 row_mask:0xf bank_mask:0xf bound_ctrl:1
	v_fma_f32 v61, v54, v57, v60
	s_nop 0
	v_add_f32_dpp v58, v58, v58 row_ror:1 row_mask:0xf bank_mask:0xf bound_ctrl:1
	v_pk_fma_f32 v[52:53], v[58:59], v[40:41], v[64:65] op_sel_hi:[0,1,1]
	v_pk_fma_f32 v[48:49], v[58:59], v[42:43], v[66:67] op_sel_hi:[0,1,1]
	v_fma_f32 v61, v58, v56, v61
	ds_read_b32 v210, v97 offset:27120
	ds_read_b64 v[220:221], v98 offset:27184
	ds_write_b32 v99, v61 offset:8704
	s_waitcnt lgkmcnt(9)
	v_pk_mul_f32 v[58:59], v[52:53], v[170:171] op_sel_hi:[0,1]
	v_pk_mul_f32 v[102:103], v[48:49], v[174:175] op_sel_hi:[0,1]
	ds_read_b128 v[32:35], v96 offset:27456
	ds_read_b128 v[36:39], v96 offset:27712
	v_pk_fma_f32 v[58:59], v[52:53], v[172:173], v[58:59] op_sel:[1,0,0]
	v_pk_fma_f32 v[102:103], v[48:49], v[176:177], v[102:103] op_sel:[1,0,0]
	ds_read_b128 v[28:31], v96 offset:27200
	ds_read_b128 v[44:47], v96 offset:28224
	ds_read_b128 v[40:43], v96 offset:27968
	v_pk_add_f32 v[58:59], v[58:59], v[102:103]
	v_pk_mul_f32 v[64:65], v[186:187], v[182:183] op_sel_hi:[0,1]
	v_pk_mul_f32 v[66:67], v[186:187], v[184:185] op_sel_hi:[0,1]
	v_add_f32_dpp v58, v58, v58 row_ror:8 row_mask:0xf bank_mask:0xf bound_ctrl:1
	v_pk_fma_f32 v[64:65], v[52:53], v[166:167], v[64:65]
	v_pk_fma_f32 v[66:67], v[48:49], v[168:169], v[66:67]
	v_add_f32_dpp v58, v58, v58 row_ror:4 row_mask:0xf bank_mask:0xf bound_ctrl:1
	v_add_f32_dpp v60, v59, v59 row_ror:8 row_mask:0xf bank_mask:0xf bound_ctrl:1
	s_nop 0
	v_add_f32_dpp v58, v58, v58 row_ror:2 row_mask:0xf bank_mask:0xf bound_ctrl:1
	v_fma_f32 v61, v186, v189, v60
	s_nop 0
	v_add_f32_dpp v58, v58, v58 row_ror:1 row_mask:0xf bank_mask:0xf bound_ctrl:1
	v_pk_fma_f32 v[52:53], v[58:59], v[178:179], v[64:65] op_sel_hi:[0,1,1]
	v_pk_fma_f32 v[48:49], v[58:59], v[180:181], v[66:67] op_sel_hi:[0,1,1]
	v_fma_f32 v61, v58, v188, v61
	ds_read_b32 v54, v97 offset:28480
	ds_read_b64 v[56:57], v98 offset:28544
	ds_write_b32 v99, v61 offset:9216
	s_waitcnt lgkmcnt(9)
	v_pk_mul_f32 v[58:59], v[52:53], v[194:195] op_sel_hi:[0,1]
	v_pk_mul_f32 v[102:103], v[48:49], v[198:199] op_sel_hi:[0,1]
	ds_read_b128 v[170:173], v96 offset:28816
	ds_read_b128 v[174:177], v96 offset:29072
	v_pk_fma_f32 v[58:59], v[52:53], v[196:197], v[58:59] op_sel:[1,0,0]
	v_pk_fma_f32 v[102:103], v[48:49], v[200:201], v[102:103] op_sel:[1,0,0]
	ds_read_b128 v[166:169], v96 offset:28560
	ds_read_b128 v[182:185], v96 offset:29584
	ds_read_b128 v[178:181], v96 offset:29328
	v_pk_add_f32 v[58:59], v[58:59], v[102:103]
	v_pk_mul_f32 v[64:65], v[210:211], v[206:207] op_sel_hi:[0,1]
	v_pk_mul_f32 v[66:67], v[210:211], v[208:209] op_sel_hi:[0,1]
	v_add_f32_dpp v58, v58, v58 row_ror:8 row_mask:0xf bank_mask:0xf bound_ctrl:1
	v_pk_fma_f32 v[64:65], v[52:53], v[190:191], v[64:65]
	v_pk_fma_f32 v[66:67], v[48:49], v[192:193], v[66:67]
	v_add_f32_dpp v58, v58, v58 row_ror:4 row_mask:0xf bank_mask:0xf bound_ctrl:1
	v_add_f32_dpp v60, v59, v59 row_ror:8 row_mask:0xf bank_mask:0xf bound_ctrl:1
	s_nop 0
	v_add_f32_dpp v58, v58, v58 row_ror:2 row_mask:0xf bank_mask:0xf bound_ctrl:1
	v_fma_f32 v61, v210, v221, v60
	s_nop 0
	v_add_f32_dpp v58, v58, v58 row_ror:1 row_mask:0xf bank_mask:0xf bound_ctrl:1
	v_pk_fma_f32 v[52:53], v[58:59], v[202:203], v[64:65] op_sel_hi:[0,1,1]
	v_pk_fma_f32 v[48:49], v[58:59], v[204:205], v[66:67] op_sel_hi:[0,1,1]
	v_fma_f32 v61, v58, v220, v61
	ds_read_b32 v186, v97 offset:29840
	ds_read_b64 v[188:189], v98 offset:29904
	ds_write_b32 v99, v61 offset:9728
	s_waitcnt lgkmcnt(9)
	v_pk_mul_f32 v[58:59], v[52:53], v[32:33] op_sel_hi:[0,1]
	v_pk_mul_f32 v[102:103], v[48:49], v[36:37] op_sel_hi:[0,1]
	ds_read_b128 v[194:197], v96 offset:30176
	ds_read_b128 v[198:201], v96 offset:30432
	v_pk_fma_f32 v[58:59], v[52:53], v[34:35], v[58:59] op_sel:[1,0,0]
	v_pk_fma_f32 v[102:103], v[48:49], v[38:39], v[102:103] op_sel:[1,0,0]
	ds_read_b128 v[190:193], v96 offset:29920
	ds_read_b128 v[206:209], v96 offset:30944
	ds_read_b128 v[202:205], v96 offset:30688
	v_pk_add_f32 v[58:59], v[58:59], v[102:103]
	v_pk_mul_f32 v[64:65], v[54:55], v[44:45] op_sel_hi:[0,1]
	v_pk_mul_f32 v[66:67], v[54:55], v[46:47] op_sel_hi:[0,1]
	v_add_f32_dpp v58, v58, v58 row_ror:8 row_mask:0xf bank_mask:0xf bound_ctrl:1
	v_pk_fma_f32 v[64:65], v[52:53], v[28:29], v[64:65]
	v_pk_fma_f32 v[66:67], v[48:49], v[30:31], v[66:67]
	v_add_f32_dpp v58, v58, v58 row_ror:4 row_mask:0xf bank_mask:0xf bound_ctrl:1
	v_add_f32_dpp v60, v59, v59 row_ror:8 row_mask:0xf bank_mask:0xf bound_ctrl:1
	s_nop 0
	v_add_f32_dpp v58, v58, v58 row_ror:2 row_mask:0xf bank_mask:0xf bound_ctrl:1
	v_fma_f32 v61, v54, v57, v60
	s_nop 0
	v_add_f32_dpp v58, v58, v58 row_ror:1 row_mask:0xf bank_mask:0xf bound_ctrl:1
	v_pk_fma_f32 v[52:53], v[58:59], v[40:41], v[64:65] op_sel_hi:[0,1,1]
	v_pk_fma_f32 v[48:49], v[58:59], v[42:43], v[66:67] op_sel_hi:[0,1,1]
	v_fma_f32 v61, v58, v56, v61
	ds_read_b32 v210, v97 offset:31200
	ds_read_b64 v[220:221], v98 offset:31264
	ds_write_b32 v99, v61 offset:10240
	s_waitcnt lgkmcnt(9)
	v_pk_mul_f32 v[58:59], v[52:53], v[170:171] op_sel_hi:[0,1]
	v_pk_mul_f32 v[102:103], v[48:49], v[174:175] op_sel_hi:[0,1]
	ds_read_b128 v[32:35], v96 offset:31536
	ds_read_b128 v[36:39], v96 offset:31792
	v_pk_fma_f32 v[58:59], v[52:53], v[172:173], v[58:59] op_sel:[1,0,0]
	v_pk_fma_f32 v[102:103], v[48:49], v[176:177], v[102:103] op_sel:[1,0,0]
	ds_read_b128 v[28:31], v96 offset:31280
	ds_read_b128 v[44:47], v96 offset:32304
	ds_read_b128 v[40:43], v96 offset:32048
	v_pk_add_f32 v[58:59], v[58:59], v[102:103]
	v_pk_mul_f32 v[64:65], v[186:187], v[182:183] op_sel_hi:[0,1]
	v_pk_mul_f32 v[66:67], v[186:187], v[184:185] op_sel_hi:[0,1]
	v_add_f32_dpp v58, v58, v58 row_ror:8 row_mask:0xf bank_mask:0xf bound_ctrl:1
	v_pk_fma_f32 v[64:65], v[52:53], v[166:167], v[64:65]
	v_pk_fma_f32 v[66:67], v[48:49], v[168:169], v[66:67]
	v_add_f32_dpp v58, v58, v58 row_ror:4 row_mask:0xf bank_mask:0xf bound_ctrl:1
	v_add_f32_dpp v60, v59, v59 row_ror:8 row_mask:0xf bank_mask:0xf bound_ctrl:1
	s_nop 0
	v_add_f32_dpp v58, v58, v58 row_ror:2 row_mask:0xf bank_mask:0xf bound_ctrl:1
	v_fma_f32 v61, v186, v189, v60
	s_nop 0
	v_add_f32_dpp v58, v58, v58 row_ror:1 row_mask:0xf bank_mask:0xf bound_ctrl:1
	v_pk_fma_f32 v[52:53], v[58:59], v[178:179], v[64:65] op_sel_hi:[0,1,1]
	v_pk_fma_f32 v[48:49], v[58:59], v[180:181], v[66:67] op_sel_hi:[0,1,1]
	v_fma_f32 v61, v58, v188, v61
	ds_read_b32 v54, v97 offset:32560
	ds_read_b64 v[56:57], v98 offset:32624
	ds_write_b32 v99, v61 offset:10752
	s_waitcnt lgkmcnt(9)
	v_pk_mul_f32 v[58:59], v[52:53], v[194:195] op_sel_hi:[0,1]
	v_pk_mul_f32 v[102:103], v[48:49], v[198:199] op_sel_hi:[0,1]
	ds_read_b128 v[170:173], v96 offset:32896
	ds_read_b128 v[174:177], v96 offset:33152
	v_pk_fma_f32 v[58:59], v[52:53], v[196:197], v[58:59] op_sel:[1,0,0]
	v_pk_fma_f32 v[102:103], v[48:49], v[200:201], v[102:103] op_sel:[1,0,0]
	ds_read_b128 v[166:169], v96 offset:32640
	ds_read_b128 v[182:185], v96 offset:33664
	ds_read_b128 v[178:181], v96 offset:33408
	v_pk_add_f32 v[58:59], v[58:59], v[102:103]
	v_pk_mul_f32 v[64:65], v[210:211], v[206:207] op_sel_hi:[0,1]
	v_pk_mul_f32 v[66:67], v[210:211], v[208:209] op_sel_hi:[0,1]
	v_add_f32_dpp v58, v58, v58 row_ror:8 row_mask:0xf bank_mask:0xf bound_ctrl:1
	v_pk_fma_f32 v[64:65], v[52:53], v[190:191], v[64:65]
	v_pk_fma_f32 v[66:67], v[48:49], v[192:193], v[66:67]
	v_add_f32_dpp v58, v58, v58 row_ror:4 row_mask:0xf bank_mask:0xf bound_ctrl:1
	v_add_f32_dpp v60, v59, v59 row_ror:8 row_mask:0xf bank_mask:0xf bound_ctrl:1
	s_nop 0
	v_add_f32_dpp v58, v58, v58 row_ror:2 row_mask:0xf bank_mask:0xf bound_ctrl:1
	v_fma_f32 v61, v210, v221, v60
	s_nop 0
	v_add_f32_dpp v58, v58, v58 row_ror:1 row_mask:0xf bank_mask:0xf bound_ctrl:1
	v_pk_fma_f32 v[52:53], v[58:59], v[202:203], v[64:65] op_sel_hi:[0,1,1]
	v_pk_fma_f32 v[48:49], v[58:59], v[204:205], v[66:67] op_sel_hi:[0,1,1]
	v_fma_f32 v61, v58, v220, v61
	ds_read_b32 v186, v97 offset:33920
	ds_read_b64 v[188:189], v98 offset:33984
	ds_write_b32 v99, v61 offset:11264
	s_waitcnt lgkmcnt(9)
	v_pk_mul_f32 v[58:59], v[52:53], v[32:33] op_sel_hi:[0,1]
	v_pk_mul_f32 v[102:103], v[48:49], v[36:37] op_sel_hi:[0,1]
	ds_read_b128 v[194:197], v96 offset:34256
	ds_read_b128 v[198:201], v96 offset:34512
	v_pk_fma_f32 v[58:59], v[52:53], v[34:35], v[58:59] op_sel:[1,0,0]
	v_pk_fma_f32 v[102:103], v[48:49], v[38:39], v[102:103] op_sel:[1,0,0]
	ds_read_b128 v[190:193], v96 offset:34000
	ds_read_b128 v[206:209], v96 offset:35024
	ds_read_b128 v[202:205], v96 offset:34768
	v_pk_add_f32 v[58:59], v[58:59], v[102:103]
	v_pk_mul_f32 v[64:65], v[54:55], v[44:45] op_sel_hi:[0,1]
	v_pk_mul_f32 v[66:67], v[54:55], v[46:47] op_sel_hi:[0,1]
	v_add_f32_dpp v58, v58, v58 row_ror:8 row_mask:0xf bank_mask:0xf bound_ctrl:1
	v_pk_fma_f32 v[64:65], v[52:53], v[28:29], v[64:65]
	v_pk_fma_f32 v[66:67], v[48:49], v[30:31], v[66:67]
	v_add_f32_dpp v58, v58, v58 row_ror:4 row_mask:0xf bank_mask:0xf bound_ctrl:1
	v_add_f32_dpp v60, v59, v59 row_ror:8 row_mask:0xf bank_mask:0xf bound_ctrl:1
	s_nop 0
	v_add_f32_dpp v58, v58, v58 row_ror:2 row_mask:0xf bank_mask:0xf bound_ctrl:1
	v_fma_f32 v61, v54, v57, v60
	s_nop 0
	v_add_f32_dpp v58, v58, v58 row_ror:1 row_mask:0xf bank_mask:0xf bound_ctrl:1
	v_pk_fma_f32 v[52:53], v[58:59], v[40:41], v[64:65] op_sel_hi:[0,1,1]
	v_pk_fma_f32 v[48:49], v[58:59], v[42:43], v[66:67] op_sel_hi:[0,1,1]
	v_fma_f32 v61, v58, v56, v61
	ds_read_b32 v210, v97 offset:35280
	ds_read_b64 v[220:221], v98 offset:35344
	ds_write_b32 v99, v61 offset:11776
	s_waitcnt lgkmcnt(9)
	v_pk_mul_f32 v[58:59], v[52:53], v[170:171] op_sel_hi:[0,1]
	v_pk_mul_f32 v[102:103], v[48:49], v[174:175] op_sel_hi:[0,1]
	ds_read_b128 v[32:35], v96 offset:35616
	ds_read_b128 v[36:39], v96 offset:35872
	v_pk_fma_f32 v[58:59], v[52:53], v[172:173], v[58:59] op_sel:[1,0,0]
	v_pk_fma_f32 v[102:103], v[48:49], v[176:177], v[102:103] op_sel:[1,0,0]
	ds_read_b128 v[28:31], v96 offset:35360
	ds_read_b128 v[44:47], v96 offset:36384
	ds_read_b128 v[40:43], v96 offset:36128
	v_pk_add_f32 v[58:59], v[58:59], v[102:103]
	v_pk_mul_f32 v[64:65], v[186:187], v[182:183] op_sel_hi:[0,1]
	v_pk_mul_f32 v[66:67], v[186:187], v[184:185] op_sel_hi:[0,1]
	v_add_f32_dpp v58, v58, v58 row_ror:8 row_mask:0xf bank_mask:0xf bound_ctrl:1
	v_pk_fma_f32 v[64:65], v[52:53], v[166:167], v[64:65]
	v_pk_fma_f32 v[66:67], v[48:49], v[168:169], v[66:67]
	v_add_f32_dpp v58, v58, v58 row_ror:4 row_mask:0xf bank_mask:0xf bound_ctrl:1
	v_add_f32_dpp v60, v59, v59 row_ror:8 row_mask:0xf bank_mask:0xf bound_ctrl:1
	s_nop 0
	v_add_f32_dpp v58, v58, v58 row_ror:2 row_mask:0xf bank_mask:0xf bound_ctrl:1
	v_fma_f32 v61, v186, v189, v60
	s_nop 0
	v_add_f32_dpp v58, v58, v58 row_ror:1 row_mask:0xf bank_mask:0xf bound_ctrl:1
	v_pk_fma_f32 v[52:53], v[58:59], v[178:179], v[64:65] op_sel_hi:[0,1,1]
	v_pk_fma_f32 v[48:49], v[58:59], v[180:181], v[66:67] op_sel_hi:[0,1,1]
	v_fma_f32 v61, v58, v188, v61
	ds_read_b32 v54, v97 offset:36640
	ds_read_b64 v[56:57], v98 offset:36704
	ds_write_b32 v99, v61 offset:12288
	s_waitcnt lgkmcnt(9)
	v_pk_mul_f32 v[58:59], v[52:53], v[194:195] op_sel_hi:[0,1]
	v_pk_mul_f32 v[102:103], v[48:49], v[198:199] op_sel_hi:[0,1]
	ds_read_b128 v[170:173], v96 offset:36976
	ds_read_b128 v[174:177], v96 offset:37232
	v_pk_fma_f32 v[58:59], v[52:53], v[196:197], v[58:59] op_sel:[1,0,0]
	v_pk_fma_f32 v[102:103], v[48:49], v[200:201], v[102:103] op_sel:[1,0,0]
	ds_read_b128 v[166:169], v96 offset:36720
	ds_read_b128 v[182:185], v96 offset:37744
	ds_read_b128 v[178:181], v96 offset:37488
	v_pk_add_f32 v[58:59], v[58:59], v[102:103]
	v_pk_mul_f32 v[64:65], v[210:211], v[206:207] op_sel_hi:[0,1]
	v_pk_mul_f32 v[66:67], v[210:211], v[208:209] op_sel_hi:[0,1]
	v_add_f32_dpp v58, v58, v58 row_ror:8 row_mask:0xf bank_mask:0xf bound_ctrl:1
	v_pk_fma_f32 v[64:65], v[52:53], v[190:191], v[64:65]
	v_pk_fma_f32 v[66:67], v[48:49], v[192:193], v[66:67]
	v_add_f32_dpp v58, v58, v58 row_ror:4 row_mask:0xf bank_mask:0xf bound_ctrl:1
	v_add_f32_dpp v60, v59, v59 row_ror:8 row_mask:0xf bank_mask:0xf bound_ctrl:1
	s_nop 0
	v_add_f32_dpp v58, v58, v58 row_ror:2 row_mask:0xf bank_mask:0xf bound_ctrl:1
	v_fma_f32 v61, v210, v221, v60
	s_nop 0
	v_add_f32_dpp v58, v58, v58 row_ror:1 row_mask:0xf bank_mask:0xf bound_ctrl:1
	v_pk_fma_f32 v[52:53], v[58:59], v[202:203], v[64:65] op_sel_hi:[0,1,1]
	v_pk_fma_f32 v[48:49], v[58:59], v[204:205], v[66:67] op_sel_hi:[0,1,1]
	v_fma_f32 v61, v58, v220, v61
	ds_read_b32 v186, v97 offset:38000
	ds_read_b64 v[188:189], v98 offset:38064
	ds_write_b32 v99, v61 offset:12800
	s_waitcnt lgkmcnt(9)
	v_pk_mul_f32 v[58:59], v[52:53], v[32:33] op_sel_hi:[0,1]
	v_pk_mul_f32 v[102:103], v[48:49], v[36:37] op_sel_hi:[0,1]
	ds_read_b128 v[194:197], v96 offset:38336
	ds_read_b128 v[198:201], v96 offset:38592
	v_pk_fma_f32 v[58:59], v[52:53], v[34:35], v[58:59] op_sel:[1,0,0]
	v_pk_fma_f32 v[102:103], v[48:49], v[38:39], v[102:103] op_sel:[1,0,0]
	ds_read_b128 v[190:193], v96 offset:38080
	ds_read_b128 v[206:209], v96 offset:39104
	ds_read_b128 v[202:205], v96 offset:38848
	v_pk_add_f32 v[58:59], v[58:59], v[102:103]
	v_pk_mul_f32 v[64:65], v[54:55], v[44:45] op_sel_hi:[0,1]
	v_pk_mul_f32 v[66:67], v[54:55], v[46:47] op_sel_hi:[0,1]
	v_add_f32_dpp v58, v58, v58 row_ror:8 row_mask:0xf bank_mask:0xf bound_ctrl:1
	v_pk_fma_f32 v[64:65], v[52:53], v[28:29], v[64:65]
	v_pk_fma_f32 v[66:67], v[48:49], v[30:31], v[66:67]
	v_add_f32_dpp v58, v58, v58 row_ror:4 row_mask:0xf bank_mask:0xf bound_ctrl:1
	v_add_f32_dpp v60, v59, v59 row_ror:8 row_mask:0xf bank_mask:0xf bound_ctrl:1
	s_nop 0
	v_add_f32_dpp v58, v58, v58 row_ror:2 row_mask:0xf bank_mask:0xf bound_ctrl:1
	v_fma_f32 v61, v54, v57, v60
	s_nop 0
	v_add_f32_dpp v58, v58, v58 row_ror:1 row_mask:0xf bank_mask:0xf bound_ctrl:1
	v_pk_fma_f32 v[52:53], v[58:59], v[40:41], v[64:65] op_sel_hi:[0,1,1]
	v_pk_fma_f32 v[48:49], v[58:59], v[42:43], v[66:67] op_sel_hi:[0,1,1]
	v_fma_f32 v61, v58, v56, v61
	ds_read_b32 v210, v97 offset:39360
	ds_read_b64 v[220:221], v98 offset:39424
	ds_write_b32 v99, v61 offset:13312
	s_waitcnt lgkmcnt(9)
	v_pk_mul_f32 v[58:59], v[52:53], v[170:171] op_sel_hi:[0,1]
	v_pk_mul_f32 v[102:103], v[48:49], v[174:175] op_sel_hi:[0,1]
	ds_read_b128 v[32:35], v96 offset:39696
	ds_read_b128 v[36:39], v96 offset:39952
	v_pk_fma_f32 v[58:59], v[52:53], v[172:173], v[58:59] op_sel:[1,0,0]
	v_pk_fma_f32 v[102:103], v[48:49], v[176:177], v[102:103] op_sel:[1,0,0]
	ds_read_b128 v[28:31], v96 offset:39440
	ds_read_b128 v[44:47], v96 offset:40464
	ds_read_b128 v[40:43], v96 offset:40208
	v_pk_add_f32 v[58:59], v[58:59], v[102:103]
	v_pk_mul_f32 v[64:65], v[186:187], v[182:183] op_sel_hi:[0,1]
	v_pk_mul_f32 v[66:67], v[186:187], v[184:185] op_sel_hi:[0,1]
	v_add_f32_dpp v58, v58, v58 row_ror:8 row_mask:0xf bank_mask:0xf bound_ctrl:1
	v_pk_fma_f32 v[64:65], v[52:53], v[166:167], v[64:65]
	v_pk_fma_f32 v[66:67], v[48:49], v[168:169], v[66:67]
	v_add_f32_dpp v58, v58, v58 row_ror:4 row_mask:0xf bank_mask:0xf bound_ctrl:1
	v_add_f32_dpp v60, v59, v59 row_ror:8 row_mask:0xf bank_mask:0xf bound_ctrl:1
	s_nop 0
	v_add_f32_dpp v58, v58, v58 row_ror:2 row_mask:0xf bank_mask:0xf bound_ctrl:1
	v_fma_f32 v61, v186, v189, v60
	s_nop 0
	v_add_f32_dpp v58, v58, v58 row_ror:1 row_mask:0xf bank_mask:0xf bound_ctrl:1
	v_pk_fma_f32 v[52:53], v[58:59], v[178:179], v[64:65] op_sel_hi:[0,1,1]
	v_pk_fma_f32 v[48:49], v[58:59], v[180:181], v[66:67] op_sel_hi:[0,1,1]
	v_fma_f32 v61, v58, v188, v61
	ds_read_b32 v54, v97 offset:40720
	ds_read_b64 v[56:57], v98 offset:40784
	ds_write_b32 v99, v61 offset:13824
	s_waitcnt lgkmcnt(9)
	v_pk_mul_f32 v[58:59], v[52:53], v[194:195] op_sel_hi:[0,1]
	v_pk_mul_f32 v[102:103], v[48:49], v[198:199] op_sel_hi:[0,1]
	ds_read_b128 v[170:173], v96 offset:41056
	ds_read_b128 v[174:177], v96 offset:41312
	v_pk_fma_f32 v[58:59], v[52:53], v[196:197], v[58:59] op_sel:[1,0,0]
	v_pk_fma_f32 v[102:103], v[48:49], v[200:201], v[102:103] op_sel:[1,0,0]
	ds_read_b128 v[166:169], v96 offset:40800
	ds_read_b128 v[182:185], v96 offset:41824
	ds_read_b128 v[178:181], v96 offset:41568
	v_pk_add_f32 v[58:59], v[58:59], v[102:103]
	v_pk_mul_f32 v[64:65], v[210:211], v[206:207] op_sel_hi:[0,1]
	v_pk_mul_f32 v[66:67], v[210:211], v[208:209] op_sel_hi:[0,1]
	v_add_f32_dpp v58, v58, v58 row_ror:8 row_mask:0xf bank_mask:0xf bound_ctrl:1
	v_pk_fma_f32 v[64:65], v[52:53], v[190:191], v[64:65]
	v_pk_fma_f32 v[66:67], v[48:49], v[192:193], v[66:67]
	v_add_f32_dpp v58, v58, v58 row_ror:4 row_mask:0xf bank_mask:0xf bound_ctrl:1
	v_add_f32_dpp v60, v59, v59 row_ror:8 row_mask:0xf bank_mask:0xf bound_ctrl:1
	s_nop 0
	v_add_f32_dpp v58, v58, v58 row_ror:2 row_mask:0xf bank_mask:0xf bound_ctrl:1
	v_fma_f32 v61, v210, v221, v60
	s_nop 0
	v_add_f32_dpp v58, v58, v58 row_ror:1 row_mask:0xf bank_mask:0xf bound_ctrl:1
	v_pk_fma_f32 v[52:53], v[58:59], v[202:203], v[64:65] op_sel_hi:[0,1,1]
	v_pk_fma_f32 v[48:49], v[58:59], v[204:205], v[66:67] op_sel_hi:[0,1,1]
	v_fma_f32 v61, v58, v220, v61
	ds_read_b32 v186, v97 offset:42080
	ds_read_b64 v[188:189], v98 offset:42144
	ds_write_b32 v99, v61 offset:14336
	s_waitcnt lgkmcnt(9)
	v_pk_mul_f32 v[58:59], v[52:53], v[32:33] op_sel_hi:[0,1]
	v_pk_mul_f32 v[102:103], v[48:49], v[36:37] op_sel_hi:[0,1]
	ds_read_b128 v[194:197], v96 offset:42416
	ds_read_b128 v[198:201], v96 offset:42672
	v_pk_fma_f32 v[58:59], v[52:53], v[34:35], v[58:59] op_sel:[1,0,0]
	v_pk_fma_f32 v[102:103], v[48:49], v[38:39], v[102:103] op_sel:[1,0,0]
	ds_read_b128 v[190:193], v96 offset:42160
	ds_read_b128 v[206:209], v96 offset:43184
	ds_read_b128 v[202:205], v96 offset:42928
	v_pk_add_f32 v[58:59], v[58:59], v[102:103]
	v_pk_mul_f32 v[64:65], v[54:55], v[44:45] op_sel_hi:[0,1]
	v_pk_mul_f32 v[66:67], v[54:55], v[46:47] op_sel_hi:[0,1]
	v_add_f32_dpp v58, v58, v58 row_ror:8 row_mask:0xf bank_mask:0xf bound_ctrl:1
	v_pk_fma_f32 v[64:65], v[52:53], v[28:29], v[64:65]
	v_pk_fma_f32 v[66:67], v[48:49], v[30:31], v[66:67]
	v_add_f32_dpp v58, v58, v58 row_ror:4 row_mask:0xf bank_mask:0xf bound_ctrl:1
	v_add_f32_dpp v60, v59, v59 row_ror:8 row_mask:0xf bank_mask:0xf bound_ctrl:1
	s_nop 0
	v_add_f32_dpp v58, v58, v58 row_ror:2 row_mask:0xf bank_mask:0xf bound_ctrl:1
	v_fma_f32 v61, v54, v57, v60
	s_nop 0
	v_add_f32_dpp v58, v58, v58 row_ror:1 row_mask:0xf bank_mask:0xf bound_ctrl:1
	v_pk_fma_f32 v[52:53], v[58:59], v[40:41], v[64:65] op_sel_hi:[0,1,1]
	v_pk_fma_f32 v[48:49], v[58:59], v[42:43], v[66:67] op_sel_hi:[0,1,1]
	v_fma_f32 v61, v58, v56, v61
	ds_read_b32 v210, v97 offset:43440
	ds_read_b64 v[220:221], v98 offset:43504
	ds_write_b32 v99, v61 offset:14848
	s_waitcnt lgkmcnt(9)
	v_pk_mul_f32 v[58:59], v[52:53], v[170:171] op_sel_hi:[0,1]
	v_pk_mul_f32 v[102:103], v[48:49], v[174:175] op_sel_hi:[0,1]
	v_pk_fma_f32 v[58:59], v[52:53], v[172:173], v[58:59] op_sel:[1,0,0]
	v_pk_fma_f32 v[102:103], v[48:49], v[176:177], v[102:103] op_sel:[1,0,0]
	v_pk_add_f32 v[58:59], v[58:59], v[102:103]
	v_pk_mul_f32 v[64:65], v[186:187], v[182:183] op_sel_hi:[0,1]
	v_pk_mul_f32 v[66:67], v[186:187], v[184:185] op_sel_hi:[0,1]
	v_add_f32_dpp v58, v58, v58 row_ror:8 row_mask:0xf bank_mask:0xf bound_ctrl:1
	v_pk_fma_f32 v[64:65], v[52:53], v[166:167], v[64:65]
	v_pk_fma_f32 v[66:67], v[48:49], v[168:169], v[66:67]
	v_add_f32_dpp v58, v58, v58 row_ror:4 row_mask:0xf bank_mask:0xf bound_ctrl:1
	v_add_f32_dpp v60, v59, v59 row_ror:8 row_mask:0xf bank_mask:0xf bound_ctrl:1
	s_nop 0
	v_add_f32_dpp v58, v58, v58 row_ror:2 row_mask:0xf bank_mask:0xf bound_ctrl:1
	v_fma_f32 v61, v186, v189, v60
	s_nop 0
	v_add_f32_dpp v58, v58, v58 row_ror:1 row_mask:0xf bank_mask:0xf bound_ctrl:1
	v_pk_fma_f32 v[52:53], v[58:59], v[178:179], v[64:65] op_sel_hi:[0,1,1]
	v_pk_fma_f32 v[48:49], v[58:59], v[180:181], v[66:67] op_sel_hi:[0,1,1]
	v_fma_f32 v61, v58, v188, v61
	ds_write_b32 v99, v61 offset:15360
	s_waitcnt lgkmcnt(2)
	v_pk_mul_f32 v[58:59], v[52:53], v[194:195] op_sel_hi:[0,1]
	v_pk_mul_f32 v[102:103], v[48:49], v[198:199] op_sel_hi:[0,1]
	v_pk_fma_f32 v[58:59], v[52:53], v[196:197], v[58:59] op_sel:[1,0,0]
	v_pk_fma_f32 v[102:103], v[48:49], v[200:201], v[102:103] op_sel:[1,0,0]
	v_pk_add_f32 v[58:59], v[58:59], v[102:103]
	v_pk_mul_f32 v[64:65], v[210:211], v[206:207] op_sel_hi:[0,1]
	v_pk_mul_f32 v[66:67], v[210:211], v[208:209] op_sel_hi:[0,1]
	v_add_f32_dpp v58, v58, v58 row_ror:8 row_mask:0xf bank_mask:0xf bound_ctrl:1
	v_pk_fma_f32 v[64:65], v[52:53], v[190:191], v[64:65]
	v_pk_fma_f32 v[66:67], v[48:49], v[192:193], v[66:67]
	v_add_f32_dpp v58, v58, v58 row_ror:4 row_mask:0xf bank_mask:0xf bound_ctrl:1
	v_add_f32_dpp v60, v59, v59 row_ror:8 row_mask:0xf bank_mask:0xf bound_ctrl:1
	s_nop 0
	v_add_f32_dpp v58, v58, v58 row_ror:2 row_mask:0xf bank_mask:0xf bound_ctrl:1
	v_fma_f32 v61, v210, v221, v60
	s_nop 0
	v_add_f32_dpp v58, v58, v58 row_ror:1 row_mask:0xf bank_mask:0xf bound_ctrl:1
	v_pk_fma_f32 v[52:53], v[58:59], v[202:203], v[64:65] op_sel_hi:[0,1,1]
	v_pk_fma_f32 v[48:49], v[58:59], v[204:205], v[66:67] op_sel_hi:[0,1,1]
	v_fma_f32 v61, v58, v220, v61
	ds_write_b32 v99, v61 offset:15872
	s_setprio 0
	s_mov_b64 s[78:79], 0
